# v21 plus prep weight transpose loop software-pipelined: next tile's decode and loads issued before this tile's LDS barrier, transposed read and store
# baseline (speedup 1.0000x reference)
.LBB0_19:
	s_load_dwordx16 s[16:31], s[0:1], 0x0
	s_andn2_b32 s14, s14, 63
	v_mbcnt_hi_u32_b32 v179, -1, v1
	v_or_b32_e32 v178, s14, v179
	v_mov_b32_e32 v16, v178
	s_waitcnt lgkmcnt(0)
	v_writelane_b32 v254, s16, 6
	s_mov_b64 s[2:3], 0
	s_nop 0
	v_writelane_b32 v254, s17, 7
	v_writelane_b32 v254, s18, 8
	v_writelane_b32 v254, s19, 9
	v_writelane_b32 v254, s20, 10
	v_writelane_b32 v254, s21, 11
	v_writelane_b32 v254, s22, 12
	v_writelane_b32 v254, s23, 13
	v_writelane_b32 v254, s24, 14
	v_writelane_b32 v254, s25, 15
	v_writelane_b32 v254, s26, 16
	v_writelane_b32 v254, s27, 17
	v_writelane_b32 v254, s28, 18
	v_writelane_b32 v254, s29, 19
	v_writelane_b32 v254, s30, 20
	v_writelane_b32 v254, s31, 21
	s_nop 0
	v_readlane_b32 s0, v254, 0
	v_readlane_b32 s1, v254, 1
	s_add_u32 s6, s0, s2
	s_addc_u32 s7, s1, s3
	s_cmpk_gt_i32 s88, 0x107f
	s_cbranch_scc1 .LBB0_42
	s_add_u32 s20, s6, 0x1900000
	s_addc_u32 s21, s7, 0
	s_add_u32 s22, s6, 0x1500000
	v_lshlrev_b32_e32 v2, 3, v16
	s_addc_u32 s23, s7, 0
	v_lshlrev_b32_e32 v0, 2, v16
	v_and_b32_e32 v2, 56, v2
	s_add_u32 s24, s6, 0x1300000
	v_ashrrev_i32_e32 v13, 4, v16
	v_and_b32_e32 v0, 60, v0
	s_movk_i32 s0, 0x104
	v_mul_u32_u24_e32 v4, 0x41, v2
	s_addc_u32 s25, s7, 0
	v_lshlrev_b32_e32 v1, 2, v0
	v_mul_lo_u32 v3, v13, s0
	v_ashrrev_i32_e32 v17, 3, v16
	v_lshlrev_b32_e32 v4, 2, v4
	s_add_u32 s26, s6, 0x1100000
	v_mov_b32_e32 v9, 0
	v_lshl_add_u32 v19, v17, 2, v4
	v_add_u32_e32 v20, v1, v3
	s_addc_u32 s27, s7, 0
	v_lshlrev_b32_e32 v8, 2, v0
	v_add_u32_e32 v21, 0x2080, v20
	v_add_u32_e32 v22, 0x2088, v20
	v_lshlrev_b32_e32 v10, 1, v2
	v_mov_b32_e32 v11, v9
	v_add_u32_e32 v23, 0x400, v19
	s_mov_b32 s28, s88
	s_mov_b32 s92, 0
	s_branch .Ltp_L
.Ltp_loop:
	v_mov_b32_e32 v36, v34
	v_mov_b32_e32 v37, v35
	s_barrier
	s_waitcnt vmcnt(0)
	v_pk_mul_f32 v[0:1], v[0:1], v[18:19] op_sel_hi:[1,0]
	ds_write2_b32 v20, v0, v1 offset1:1
	v_pk_mul_f32 v[0:1], v[2:3], v[18:19] op_sel_hi:[1,0]
	ds_write2_b32 v20, v0, v1 offset0:2 offset1:3
	v_pk_mul_f32 v[0:1], v[4:5], v[12:13] op_sel_hi:[1,0]
	ds_write2_b32 v21, v0, v1 offset1:1
	v_pk_mul_f32 v[0:1], v[6:7], v[12:13] op_sel_hi:[1,0]
	ds_write2_b32 v22, v0, v1 offset1:1
	s_add_i32 s28, s28, s90
	s_cmpk_gt_i32 s28, 0x107f
	s_cbranch_scc1 .Ltp_last
	s_mov_b32 s92, 1

.LBB0_38:
	s_lshr_b32 s18, s31, 6
	v_cvt_f32_i32_e32 v0, s18
	s_sext_i32_i16 s12, s30
	v_cvt_f32_i32_e32 v1, s12
	s_ashr_i32 s12, s12, 30
	v_rcp_iflag_f32_e32 v2, v0
	s_or_b32 s19, s12, 1
	v_mul_f32_e32 v2, v1, v2
	v_trunc_f32_e32 v2, v2
	v_fma_f32 v1, -v2, v0, v1
	v_cvt_i32_f32_e32 v2, v2
	v_cmp_ge_f32_e64 s[12:13], |v1|, v0
	s_and_b64 s[12:13], s[12:13], exec
	s_cselect_b32 s12, s19, 0
	v_readfirstlane_b32 s13, v2
	s_add_i32 s12, s13, s12
	s_sext_i32_i16 s13, s12
	s_mul_i32 s12, s12, s18
	s_sub_i32 s12, s30, s12
	s_sext_i32_i16 s18, s12
	s_lshl_b32 s18, s18, 6
	s_ashr_i32 s19, s18, 31
	s_lshl_b32 s12, s13, 6
	s_lshl_b64 s[34:35], s[18:19], 2
	s_add_u32 s10, s10, s34
	s_addc_u32 s11, s11, s35
	v_add_u32_e32 v6, s12, v13
	v_lshl_add_u64 v[4:5], s[10:11], 0, v[8:9]
	v_mad_u64_u32 v[0:1], s[10:11], v6, s31, 0
	v_ashrrev_i32_e32 v7, 31, v6
	v_mov_b32_e32 v2, v1
	v_mad_u64_u32 v[2:3], s[10:11], v7, s31, v[2:3]
	v_mov_b32_e32 v1, v2
	v_lshl_add_u64 v[0:1], v[0:1], 2, v[4:5]
	global_load_dwordx4 v[0:3], v[0:1], off
	s_cmp_lg_u64 s[14:15], 0
	s_cselect_b64 s[10:11], -1, 0
	s_cmp_eq_u64 s[14:15], 0
	v_mov_b32_e32 v12, 1.0
	v_lshl_add_u64 v[14:15], v[6:7], 2, s[14:15]
	v_mov_b32_e32 v18, 1.0
	s_cbranch_scc1 .LBB0_40
	global_load_dword v18, v[14:15], off
.LBB0_40:
	v_add_u32_e32 v6, 32, v6
	v_ashrrev_i32_e32 v25, 31, v6
	v_mad_u64_u32 v[6:7], s[14:15], v6, s31, 0
	v_mov_b32_e32 v24, v7
	v_mad_u64_u32 v[24:25], s[14:15], v25, s31, v[24:25]
	v_mov_b32_e32 v7, v24
	v_lshl_add_u64 v[4:5], v[6:7], 2, v[4:5]
	global_load_dwordx4 v[4:7], v[4:5], off
	s_andn2_b64 vcc, exec, s[10:11]
	s_cbranch_vccnz .Ltp_ng
	global_load_dword v12, v[14:15], off offset:128
.Ltp_ng:
	v_add_u32_e32 v38, s18, v17
	v_ashrrev_i32_e32 v39, 31, v38
	v_mul_lo_u32 v40, s16, v39
	v_mul_lo_u32 v41, s17, v38
	v_mad_u64_u32 v[38:39], s[10:11], s16, v38, 0
	v_add3_u32 v39, v39, v40, v41
	s_ashr_i32 s13, s12, 31
	v_lshl_add_u64 v[38:39], v[38:39], 1, s[0:1]
	v_lshl_add_u64 v[38:39], s[12:13], 1, v[38:39]
	v_lshl_add_u64 v[34:35], v[38:39], 0, v[10:11]
	s_cmp_eq_u32 s92, 0
	s_cbranch_scc1 .Ltp_loop
	s_waitcnt lgkmcnt(0)
	s_barrier
	ds_read2_b32 v[26:27], v19 offset1:65
	ds_read2_b32 v[28:29], v19 offset0:130 offset1:195
	ds_read2_b32 v[30:31], v23 offset0:4 offset1:69
	ds_read2_b32 v[32:33], v23 offset0:134 offset1:199
	s_waitcnt lgkmcnt(3)
	v_cvt_pk_bf16_f32 v26, v26, v27
	s_waitcnt lgkmcnt(2)
	v_cvt_pk_bf16_f32 v27, v28, v29
	s_waitcnt lgkmcnt(1)
	v_cvt_pk_bf16_f32 v28, v30, v31
	s_waitcnt lgkmcnt(0)
	v_cvt_pk_bf16_f32 v29, v32, v33
	global_store_dwordx4 v[36:37], v[26:29], off
	s_branch .Ltp_loop
.Ltp_last:
	s_waitcnt lgkmcnt(0)
	s_barrier
	ds_read2_b32 v[26:27], v19 offset1:65
	ds_read2_b32 v[28:29], v19 offset0:130 offset1:195
	ds_read2_b32 v[30:31], v23 offset0:4 offset1:69
	ds_read2_b32 v[32:33], v23 offset0:134 offset1:199
	s_waitcnt lgkmcnt(3)
	v_cvt_pk_bf16_f32 v26, v26, v27
	s_waitcnt lgkmcnt(2)
	v_cvt_pk_bf16_f32 v27, v28, v29
	s_waitcnt lgkmcnt(1)
	v_cvt_pk_bf16_f32 v28, v30, v31
	s_waitcnt lgkmcnt(0)
	v_cvt_pk_bf16_f32 v29, v32, v33
	global_store_dwordx4 v[36:37], v[26:29], off
